# cache policy: the bf16 input-copy stores of P0 also non-temporal
# speedup vs baseline: 1.0013x; 1.0013x over previous
.LBB0_122:
	s_or_b64 exec, exec, s[0:1]
	v_cvt_pk_bf16_f32 v2, v2, v3
	v_cvt_pk_bf16_f32 v3, v4, v5
	global_store_dwordx2 v[28:29], v[2:3], off nt
	v_cvt_pk_bf16_f32 v2, v6, v7
	v_cvt_pk_bf16_f32 v3, v8, v9
	global_store_dwordx2 v[28:29], v[2:3], off offset:512 nt
	v_cvt_pk_bf16_f32 v2, v10, v11
	v_cvt_pk_bf16_f32 v3, v12, v13
	v_lshl_add_u64 v[18:19], v[18:19], 0, v[20:21]
	global_store_dwordx2 v[28:29], v[2:3], off offset:1024 nt
	v_cvt_pk_bf16_f32 v2, v14, v15
	v_cvt_pk_bf16_f32 v3, v16, v17
	v_cmp_lt_i32_e64 s[0:1], s9, v18
	global_store_dwordx2 v[28:29], v[2:3], off offset:1536 nt
	v_lshl_add_u64 v[24:25], v[24:25], 0, v[26:27]
	s_or_b64 s[6:7], s[0:1], s[6:7]
	v_lshl_add_u64 v[28:29], v[28:29], 0, v[30:31]
	s_andn2_b64 exec, exec, s[6:7]
	s_cbranch_execz .LBB0_125
